# v39 plus the XCD-aware barrier used after phase 0 in place of the cooperative-groups grid sync
# speedup vs baseline: 1.0153x; 1.0085x over previous
; __device__ __forceinline__ unsigned xb_add(unsigned* p, unsigned v) { return __hip_atomic_fetch_add(p, v, __ATOMIC_RELAXED, __HIP_MEMORY_SCOPE_AGENT); }
; __device__ __forceinline__ void xcd_barrier(const XcdBarrier& b) {
;     asm volatile("s_waitcnt vmcnt(0)" ::: "memory");
;     __syncthreads();
;     if (threadIdx.x == 0) {
;         unsigned* bar = b.bar;
;         __builtin_amdgcn_s_waitcnt(0);
;         unsigned nloc = b.st[0], nx = b.st[1];
;         if (nloc == 0u) { xcd_barrier_complete(bar, b.x, nloc, nx); b.st[0] = nloc; b.st[1] = nx; }
;         const unsigned old = xb_add(&bar[XB_XSUB(b.x)], 1u);
;         const unsigned gen = old / nloc;
;         if (old + 1u == (gen + 1u) * nloc) {
; __global__ void __launch_bounds__(512, 2) fwd_megakernel(Args a) {
;     ...
;         if (ph + 1 < a.ph_hi) { if (ph == 0) grid.sync(); else xcd_barrier(bar); }
.LBB0_504:
	v_readlane_b32 s4, v253, 6
	v_readlane_b32 s5, v253, 7
	s_add_i32 s4, s35, 1
	v_writelane_b32 v253, s4, 6
	s_cmp_ge_i32 s4, s5
	v_readlane_b32 s6, v252, 7
	v_writelane_b32 v253, s5, 7
	s_mov_b64 s[4:5], -1
	v_readlane_b32 s7, v252, 8
	s_cbranch_scc1 .LBB0_12
	s_cmp_lg_u32 s35, 0
	s_nop 0
	s_waitcnt vmcnt(0)
	s_waitcnt vmcnt(0) lgkmcnt(0)
	s_barrier
	s_mov_b64 s[4:5], exec
	v_readlane_b32 s6, v253, 8
	v_readlane_b32 s7, v253, 9
	s_and_b64 s[6:7], s[4:5], s[6:7]
	s_mov_b64 exec, s[6:7]
	s_cbranch_execz .LBB0_558
	v_readlane_b32 s0, v254, 47
	s_waitcnt vmcnt(0) expcnt(0) lgkmcnt(0)
	s_nop 0
	v_mov_b32_e32 v1, s0
	ds_read_b32 v3, v1
	v_readlane_b32 s0, v254, 48
	s_waitcnt lgkmcnt(0)
	v_cmp_ne_u32_e32 vcc, 0, v3
	v_mov_b32_e32 v1, s0
	ds_read_b32 v2, v1
	s_cbranch_vccnz .LBB0_522
	s_mov_b32 s0, 1
	s_branch .LBB0_510
